# FFN_UP epilogue: all 8 stores issued together at the end after one vmcnt(0) (no counted wait over stores); RESID top drain removed
# baseline (speedup 1.0000x reference)
; DI u32x2 pk4(f32x4 v) { u32x2 r; r.x = cvt_pk(v[0], v[1]); r.y = cvt_pk(v[2], v[3]); return r; }
; DI float fexp2(float x) { return __builtin_amdgcn_exp2f(x); }
; DI float frcp(float x) { return __builtin_amdgcn_rcpf(x); }
; DI void gemm_phase(LAS unsigned char* lds, const GemmDesc& d, float* __restrict__ X) {
;     ...
;     if (EPI_ON(EPI_FFN_UP)) {
; #pragma unroll
;       for (int ai = 0; ai < 2; ++ai)
; #pragma unroll
;         for (int m = 0; m < 4; ++m) {
;           const int row = pm * 256 + 128 * ai + 16 * m + rb; const float rs = rsl[128 * ai + 16 * m + rb]; const float c1 = -rs * LOG2E, c2 = rs * rs;
;           u32x2 hp[2];
; #pragma unroll
;           for (int n = 0; n < 2; ++n) {
;             const f32x4 G = acc[ai][0][m][n], U = acc[ai][1][m][n]; const f32x4 tt = G * c1; f32x4 ee;
; #pragma unroll
;             for (int j = 0; j < 4; ++j) ee[j] = fexp2(tt[j]);
;             const f32x4 dn = ee + 1.f; f32x4 rr;
; #pragma unroll
;             for (int j = 0; j < 4; ++j) rr[j] = frcp(dn[j]);
;             hp[n] = pk4((G * U) * (rr * c2));
;           }
;           { const int hc = pn * 128 + cb;
;             u32x4 hw; hw.x = hp[0].x; hw.y = hp[0].y; hw.z = hp[1].x; hw.w = hp[1].y;
;             *(u32x4*)(d.O0 + (size_t)(row >> 8) * (256 * FF) + (size_t)(hc >> 6) * (256 * 64) + (row & 255) * 64 + (hc & 63)) = hw; }
.LBB0_519:
	s_andn2_b64 vcc, exec, s[44:45]
	s_cbranch_vccnz .LBB0_542
	s_cmp_lg_u32 s24, 1
	s_mov_b64 s[44:45], -1
	s_cbranch_scc0 .LBB0_522
	v_lshl_add_u32 v141, v163, 2, s38
	ds_read_b32 v132, v141
	ds_read_b32 v133, v141 offset:64
	ds_read_b32 v134, v141 offset:128
	ds_read_b32 v135, v141 offset:192
	ds_read_b32 v136, v141 offset:512
	ds_read_b32 v137, v141 offset:576
	ds_read_b32 v138, v141 offset:640
	ds_read_b32 v139, v141 offset:704
	s_lshl_b32 s6, s68, 7
	v_lshl_add_u32 v0, s97, 8, v163
	s_or_b32 s6, s21, s6
	v_lshrrev_b32_e32 v0, 8, v0
	s_ashr_i32 s14, s6, 6
	v_mul_hi_i32_i24_e32 v131, 0x160000, v0
	v_mul_i32_i24_e32 v130, 0x160000, v0
	s_ashr_i32 s15, s14, 31
	v_lshl_add_u64 v[130:131], s[28:29], 0, v[130:131]
	s_lshl_b64 s[44:45], s[14:15], 15
	v_lshlrev_b32_e32 v0, 7, v163
	v_and_b32_e32 v144, 56, v182
	v_lshl_add_u64 v[130:131], v[130:131], 0, s[44:45]
	v_and_b32_e32 v0, 0x6780, v0
	v_lshl_add_u64 v[130:131], v[130:131], 0, v[0:1]
	v_lshlrev_b32_e32 v0, 1, v144
	v_mov_b32_e32 v144, 1.0
	v_lshl_add_u64 v[130:131], v[130:131], 0, v[0:1]
	v_mov_b32_e32 v145, 1.0
	s_mov_b32 s15, 0
	s_waitcnt lgkmcnt(0)
	v_mul_f32_e32 v140, 0xbfb8aa3b, v132
	v_mul_f32_e32 v142, v132, v132
	v_pk_mul_f32 v[118:119], v[126:127], v[118:119]
	v_pk_mul_f32 v[120:121], v[128:129], v[120:121]
	v_pk_mul_f32 v[114:115], v[122:123], v[114:115]
	v_pk_mul_f32 v[116:117], v[124:125], v[116:117]
	v_pk_mul_f32 v[126:127], v[126:127], v[140:141] op_sel_hi:[1,0]
	v_pk_mul_f32 v[128:129], v[128:129], v[140:141] op_sel_hi:[1,0]
	v_pk_mul_f32 v[122:123], v[122:123], v[140:141] op_sel_hi:[1,0]
	v_pk_mul_f32 v[124:125], v[124:125], v[140:141] op_sel_hi:[1,0]
	v_exp_f32_e32 v126, v126
	v_exp_f32_e32 v127, v127
	v_exp_f32_e32 v128, v128
	v_exp_f32_e32 v129, v129
	v_exp_f32_e32 v122, v122
	v_exp_f32_e32 v123, v123
	v_exp_f32_e32 v124, v124
	v_exp_f32_e32 v125, v125
	v_pk_add_f32 v[126:127], v[126:127], v[144:145]
	v_pk_add_f32 v[128:129], v[128:129], v[144:145]
	v_pk_add_f32 v[122:123], v[122:123], v[144:145]
	v_pk_add_f32 v[124:125], v[124:125], v[144:145]
	v_rcp_f32_e32 v126, v126
	v_rcp_f32_e32 v127, v127
	v_rcp_f32_e32 v128, v128
	v_rcp_f32_e32 v129, v129
	v_rcp_f32_e32 v122, v122
	v_rcp_f32_e32 v123, v123
	v_rcp_f32_e32 v124, v124
	v_rcp_f32_e32 v125, v125
	v_pk_mul_f32 v[126:127], v[142:143], v[126:127] op_sel_hi:[0,1]
	v_pk_mul_f32 v[128:129], v[142:143], v[128:129] op_sel_hi:[0,1]
	v_pk_mul_f32 v[122:123], v[142:143], v[122:123] op_sel_hi:[0,1]
	v_pk_mul_f32 v[124:125], v[142:143], v[124:125] op_sel_hi:[0,1]
	v_pk_mul_f32 v[126:127], v[118:119], v[126:127]
	v_pk_mul_f32 v[128:129], v[120:121], v[128:129]
	v_pk_mul_f32 v[122:123], v[114:115], v[122:123]
	v_pk_mul_f32 v[124:125], v[116:117], v[124:125]
	v_cvt_pk_bf16_f32 v126, v126, v127
	v_cvt_pk_bf16_f32 v127, v128, v129
	v_cvt_pk_bf16_f32 v128, v122, v123
	v_cvt_pk_bf16_f32 v129, v124, v125
	v_mul_f32_e32 v140, 0xbfb8aa3b, v133
	v_mul_f32_e32 v142, v133, v133
	v_pk_mul_f32 v[102:103], v[110:111], v[102:103]
	v_pk_mul_f32 v[104:105], v[112:113], v[104:105]
	v_pk_mul_f32 v[98:99], v[106:107], v[98:99]
	v_pk_mul_f32 v[100:101], v[108:109], v[100:101]
	v_pk_mul_f32 v[110:111], v[110:111], v[140:141] op_sel_hi:[1,0]
	v_pk_mul_f32 v[112:113], v[112:113], v[140:141] op_sel_hi:[1,0]
	v_pk_mul_f32 v[106:107], v[106:107], v[140:141] op_sel_hi:[1,0]
	v_pk_mul_f32 v[108:109], v[108:109], v[140:141] op_sel_hi:[1,0]
	v_exp_f32_e32 v110, v110
	v_exp_f32_e32 v111, v111
	v_exp_f32_e32 v112, v112
	v_exp_f32_e32 v113, v113
	v_exp_f32_e32 v106, v106
	v_exp_f32_e32 v107, v107
	v_exp_f32_e32 v108, v108
	v_exp_f32_e32 v109, v109
	v_pk_add_f32 v[110:111], v[110:111], v[144:145]
	v_pk_add_f32 v[112:113], v[112:113], v[144:145]
	v_pk_add_f32 v[106:107], v[106:107], v[144:145]
	v_pk_add_f32 v[108:109], v[108:109], v[144:145]
	v_rcp_f32_e32 v110, v110
	v_rcp_f32_e32 v111, v111
	v_rcp_f32_e32 v112, v112
	v_rcp_f32_e32 v113, v113
	v_rcp_f32_e32 v106, v106
	v_rcp_f32_e32 v107, v107
	v_rcp_f32_e32 v108, v108
	v_rcp_f32_e32 v109, v109
	v_pk_mul_f32 v[110:111], v[142:143], v[110:111] op_sel_hi:[0,1]
	v_pk_mul_f32 v[112:113], v[142:143], v[112:113] op_sel_hi:[0,1]
	v_pk_mul_f32 v[106:107], v[142:143], v[106:107] op_sel_hi:[0,1]
	v_pk_mul_f32 v[108:109], v[142:143], v[108:109] op_sel_hi:[0,1]
	v_pk_mul_f32 v[110:111], v[102:103], v[110:111]
	v_pk_mul_f32 v[112:113], v[104:105], v[112:113]
	v_pk_mul_f32 v[106:107], v[98:99], v[106:107]
	v_pk_mul_f32 v[108:109], v[100:101], v[108:109]
	v_cvt_pk_bf16_f32 v110, v110, v111
	v_cvt_pk_bf16_f32 v111, v112, v113
	v_cvt_pk_bf16_f32 v112, v106, v107
	v_cvt_pk_bf16_f32 v113, v108, v109
	s_movk_i32 s14, 0x1000
	v_lshl_add_u64 v[114:115], v[130:131], 0, s[14:15]
	v_mul_f32_e32 v140, 0xbfb8aa3b, v134
	v_mul_f32_e32 v142, v134, v134
	v_pk_mul_f32 v[86:87], v[94:95], v[86:87]
	v_pk_mul_f32 v[88:89], v[96:97], v[88:89]
	v_pk_mul_f32 v[82:83], v[90:91], v[82:83]
	v_pk_mul_f32 v[84:85], v[92:93], v[84:85]
	v_pk_mul_f32 v[94:95], v[94:95], v[140:141] op_sel_hi:[1,0]
	v_pk_mul_f32 v[96:97], v[96:97], v[140:141] op_sel_hi:[1,0]
	v_pk_mul_f32 v[90:91], v[90:91], v[140:141] op_sel_hi:[1,0]
	v_pk_mul_f32 v[92:93], v[92:93], v[140:141] op_sel_hi:[1,0]
	v_exp_f32_e32 v94, v94
	v_exp_f32_e32 v95, v95
	v_exp_f32_e32 v96, v96
	v_exp_f32_e32 v97, v97
	v_exp_f32_e32 v90, v90
	v_exp_f32_e32 v91, v91
	v_exp_f32_e32 v92, v92
	v_exp_f32_e32 v93, v93
	v_pk_add_f32 v[94:95], v[94:95], v[144:145]
	v_pk_add_f32 v[96:97], v[96:97], v[144:145]
	v_pk_add_f32 v[90:91], v[90:91], v[144:145]
	v_pk_add_f32 v[92:93], v[92:93], v[144:145]
	v_rcp_f32_e32 v94, v94
	v_rcp_f32_e32 v95, v95
	v_rcp_f32_e32 v96, v96
	v_rcp_f32_e32 v97, v97
; DI u32x2 pk4(f32x4 v) { u32x2 r; r.x = cvt_pk(v[0], v[1]); r.y = cvt_pk(v[2], v[3]); return r; }
; DI float fexp2(float x) { return __builtin_amdgcn_exp2f(x); }
; DI float frcp(float x) { return __builtin_amdgcn_rcpf(x); }
; DI void gemm_phase(LAS unsigned char* lds, const GemmDesc& d, float* __restrict__ X) {
;     ...
;           const int row = pm * 256 + 128 * ai + 16 * m + rb; const float rs = rsl[128 * ai + 16 * m + rb]; const float c1 = -rs * LOG2E, c2 = rs * rs;
;           u32x2 hp[2];
; #pragma unroll
;           for (int n = 0; n < 2; ++n) {
;             const f32x4 G = acc[ai][0][m][n], U = acc[ai][1][m][n]; const f32x4 tt = G * c1; f32x4 ee;
; #pragma unroll
;             for (int j = 0; j < 4; ++j) ee[j] = fexp2(tt[j]);
;             const f32x4 dn = ee + 1.f; f32x4 rr;
; #pragma unroll
;             for (int j = 0; j < 4; ++j) rr[j] = frcp(dn[j]);
;             hp[n] = pk4((G * U) * (rr * c2));
;           }
;           { const int hc = pn * 128 + cb;
;             u32x4 hw; hw.x = hp[0].x; hw.y = hp[0].y; hw.z = hp[1].x; hw.w = hp[1].y;
;             *(u32x4*)(d.O0 + (size_t)(row >> 8) * (256 * FF) + (size_t)(hc >> 6) * (256 * 64) + (row & 255) * 64 + (hc & 63)) = hw; }
	v_rcp_f32_e32 v90, v90
	v_rcp_f32_e32 v91, v91
	v_rcp_f32_e32 v92, v92
	v_rcp_f32_e32 v93, v93
	v_pk_mul_f32 v[94:95], v[142:143], v[94:95] op_sel_hi:[0,1]
	v_pk_mul_f32 v[96:97], v[142:143], v[96:97] op_sel_hi:[0,1]
	v_pk_mul_f32 v[90:91], v[142:143], v[90:91] op_sel_hi:[0,1]
	v_pk_mul_f32 v[92:93], v[142:143], v[92:93] op_sel_hi:[0,1]
	v_pk_mul_f32 v[94:95], v[86:87], v[94:95]
	v_pk_mul_f32 v[96:97], v[88:89], v[96:97]
	v_pk_mul_f32 v[90:91], v[82:83], v[90:91]
	v_pk_mul_f32 v[92:93], v[84:85], v[92:93]
	v_cvt_pk_bf16_f32 v94, v94, v95
	v_cvt_pk_bf16_f32 v95, v96, v97
	v_cvt_pk_bf16_f32 v96, v90, v91
	v_cvt_pk_bf16_f32 v97, v92, v93
	v_mul_f32_e32 v140, 0xbfb8aa3b, v135
	v_mul_f32_e32 v142, v135, v135
	v_pk_mul_f32 v[70:71], v[78:79], v[70:71]
	v_pk_mul_f32 v[72:73], v[80:81], v[72:73]
	v_pk_mul_f32 v[66:67], v[74:75], v[66:67]
	v_pk_mul_f32 v[68:69], v[76:77], v[68:69]
	v_pk_mul_f32 v[78:79], v[78:79], v[140:141] op_sel_hi:[1,0]
	v_pk_mul_f32 v[80:81], v[80:81], v[140:141] op_sel_hi:[1,0]
	v_pk_mul_f32 v[74:75], v[74:75], v[140:141] op_sel_hi:[1,0]
	v_pk_mul_f32 v[76:77], v[76:77], v[140:141] op_sel_hi:[1,0]
	v_exp_f32_e32 v78, v78
	v_exp_f32_e32 v79, v79
	v_exp_f32_e32 v80, v80
	v_exp_f32_e32 v81, v81
	v_exp_f32_e32 v74, v74
	v_exp_f32_e32 v75, v75
	v_exp_f32_e32 v76, v76
	v_exp_f32_e32 v77, v77
	v_pk_add_f32 v[78:79], v[78:79], v[144:145]
	v_pk_add_f32 v[80:81], v[80:81], v[144:145]
	v_pk_add_f32 v[74:75], v[74:75], v[144:145]
	v_pk_add_f32 v[76:77], v[76:77], v[144:145]
	v_rcp_f32_e32 v78, v78
	v_rcp_f32_e32 v79, v79
	v_rcp_f32_e32 v80, v80
	v_rcp_f32_e32 v81, v81
	v_rcp_f32_e32 v74, v74
	v_rcp_f32_e32 v75, v75
	v_rcp_f32_e32 v76, v76
	v_rcp_f32_e32 v77, v77
	v_pk_mul_f32 v[78:79], v[142:143], v[78:79] op_sel_hi:[0,1]
	v_pk_mul_f32 v[80:81], v[142:143], v[80:81] op_sel_hi:[0,1]
	v_pk_mul_f32 v[74:75], v[142:143], v[74:75] op_sel_hi:[0,1]
	v_pk_mul_f32 v[76:77], v[142:143], v[76:77] op_sel_hi:[0,1]
	v_pk_mul_f32 v[78:79], v[70:71], v[78:79]
	v_pk_mul_f32 v[80:81], v[72:73], v[80:81]
	v_pk_mul_f32 v[74:75], v[66:67], v[74:75]
	v_pk_mul_f32 v[76:77], v[68:69], v[76:77]
	v_cvt_pk_bf16_f32 v78, v78, v79
	v_cvt_pk_bf16_f32 v79, v80, v81
	v_cvt_pk_bf16_f32 v80, v74, v75
	v_cvt_pk_bf16_f32 v81, v76, v77
	s_movk_i32 s14, 0x4000
	v_lshl_add_u64 v[116:117], v[130:131], 0, s[14:15]
	v_mul_f32_e32 v140, 0xbfb8aa3b, v136
	v_mul_f32_e32 v142, v136, v136
	v_pk_mul_f32 v[54:55], v[62:63], v[54:55]
	v_pk_mul_f32 v[56:57], v[64:65], v[56:57]
	v_pk_mul_f32 v[50:51], v[58:59], v[50:51]
	v_pk_mul_f32 v[52:53], v[60:61], v[52:53]
	v_pk_mul_f32 v[62:63], v[62:63], v[140:141] op_sel_hi:[1,0]
	v_pk_mul_f32 v[64:65], v[64:65], v[140:141] op_sel_hi:[1,0]
	v_pk_mul_f32 v[58:59], v[58:59], v[140:141] op_sel_hi:[1,0]
	v_pk_mul_f32 v[60:61], v[60:61], v[140:141] op_sel_hi:[1,0]
	v_exp_f32_e32 v62, v62
	v_exp_f32_e32 v63, v63
	v_exp_f32_e32 v64, v64
	v_exp_f32_e32 v65, v65
	v_exp_f32_e32 v58, v58
	v_exp_f32_e32 v59, v59
	v_exp_f32_e32 v60, v60
	v_exp_f32_e32 v61, v61
	v_pk_add_f32 v[62:63], v[62:63], v[144:145]
	v_pk_add_f32 v[64:65], v[64:65], v[144:145]
	v_pk_add_f32 v[58:59], v[58:59], v[144:145]
	v_pk_add_f32 v[60:61], v[60:61], v[144:145]
	v_rcp_f32_e32 v62, v62
	v_rcp_f32_e32 v63, v63
	v_rcp_f32_e32 v64, v64
	v_rcp_f32_e32 v65, v65
	v_rcp_f32_e32 v58, v58
	v_rcp_f32_e32 v59, v59
	v_rcp_f32_e32 v60, v60
	v_rcp_f32_e32 v61, v61
	v_pk_mul_f32 v[62:63], v[142:143], v[62:63] op_sel_hi:[0,1]
	v_pk_mul_f32 v[64:65], v[142:143], v[64:65] op_sel_hi:[0,1]
	v_pk_mul_f32 v[58:59], v[142:143], v[58:59] op_sel_hi:[0,1]
	v_pk_mul_f32 v[60:61], v[142:143], v[60:61] op_sel_hi:[0,1]
	v_pk_mul_f32 v[62:63], v[54:55], v[62:63]
	v_pk_mul_f32 v[64:65], v[56:57], v[64:65]
	v_pk_mul_f32 v[58:59], v[50:51], v[58:59]
	v_pk_mul_f32 v[60:61], v[52:53], v[60:61]
	v_cvt_pk_bf16_f32 v62, v62, v63
	v_cvt_pk_bf16_f32 v63, v64, v65
	v_cvt_pk_bf16_f32 v64, v58, v59
	v_cvt_pk_bf16_f32 v65, v60, v61
	v_mul_f32_e32 v140, 0xbfb8aa3b, v137
	v_mul_f32_e32 v142, v137, v137
	v_pk_mul_f32 v[38:39], v[46:47], v[38:39]
	v_pk_mul_f32 v[40:41], v[48:49], v[40:41]
	v_pk_mul_f32 v[34:35], v[42:43], v[34:35]
	v_pk_mul_f32 v[36:37], v[44:45], v[36:37]
	v_pk_mul_f32 v[46:47], v[46:47], v[140:141] op_sel_hi:[1,0]
	v_pk_mul_f32 v[48:49], v[48:49], v[140:141] op_sel_hi:[1,0]
	v_pk_mul_f32 v[42:43], v[42:43], v[140:141] op_sel_hi:[1,0]
	v_pk_mul_f32 v[44:45], v[44:45], v[140:141] op_sel_hi:[1,0]
	v_exp_f32_e32 v46, v46
	v_exp_f32_e32 v47, v47
	v_exp_f32_e32 v48, v48
	v_exp_f32_e32 v49, v49
	v_exp_f32_e32 v42, v42
	v_exp_f32_e32 v43, v43
	v_exp_f32_e32 v44, v44
	v_exp_f32_e32 v45, v45
	v_pk_add_f32 v[46:47], v[46:47], v[144:145]
	v_pk_add_f32 v[48:49], v[48:49], v[144:145]
	v_pk_add_f32 v[42:43], v[42:43], v[144:145]
	v_pk_add_f32 v[44:45], v[44:45], v[144:145]
	v_rcp_f32_e32 v46, v46
	v_rcp_f32_e32 v47, v47
	v_rcp_f32_e32 v48, v48
	v_rcp_f32_e32 v49, v49
; #define LAS __attribute__((address_space(3)))
; DI u32x2 pk4(f32x4 v) { u32x2 r; r.x = cvt_pk(v[0], v[1]); r.y = cvt_pk(v[2], v[3]); return r; }
; DI float fexp2(float x) { return __builtin_amdgcn_exp2f(x); }
; DI float frcp(float x) { return __builtin_amdgcn_rcpf(x); }
; DI void gemm_phase(LAS unsigned char* lds, const GemmDesc& d, float* __restrict__ X) {
;     ...
;           const int row = pm * 256 + 128 * ai + 16 * m + rb; const float rs = rsl[128 * ai + 16 * m + rb]; const float c1 = -rs * LOG2E, c2 = rs * rs;
;           u32x2 hp[2];
; #pragma unroll
;           for (int n = 0; n < 2; ++n) {
;             const f32x4 G = acc[ai][0][m][n], U = acc[ai][1][m][n]; const f32x4 tt = G * c1; f32x4 ee;
; #pragma unroll
;             for (int j = 0; j < 4; ++j) ee[j] = fexp2(tt[j]);
;             const f32x4 dn = ee + 1.f; f32x4 rr;
; #pragma unroll
;             for (int j = 0; j < 4; ++j) rr[j] = frcp(dn[j]);
;             hp[n] = pk4((G * U) * (rr * c2));
;           }
;           { const int hc = pn * 128 + cb;
;             u32x4 hw; hw.x = hp[0].x; hw.y = hp[0].y; hw.z = hp[1].x; hw.w = hp[1].y;
;             *(u32x4*)(d.O0 + (size_t)(row >> 8) * (256 * FF) + (size_t)(hc >> 6) * (256 * 64) + (row & 255) * 64 + (hc & 63)) = hw; }
;     ...
;     if (nrs) ((LAS float*)(lds + 131072 + ((ui + 1) & 1) * 1024))[ktid] = rsqrtf(((q0 + q1) + (q2 + q3)) * d.inv_dim + EPS);
	v_rcp_f32_e32 v42, v42
	v_rcp_f32_e32 v43, v43
	v_rcp_f32_e32 v44, v44
	v_rcp_f32_e32 v45, v45
	v_pk_mul_f32 v[46:47], v[142:143], v[46:47] op_sel_hi:[0,1]
	v_pk_mul_f32 v[48:49], v[142:143], v[48:49] op_sel_hi:[0,1]
	v_pk_mul_f32 v[42:43], v[142:143], v[42:43] op_sel_hi:[0,1]
	v_pk_mul_f32 v[44:45], v[142:143], v[44:45] op_sel_hi:[0,1]
	v_pk_mul_f32 v[46:47], v[38:39], v[46:47]
	v_pk_mul_f32 v[48:49], v[40:41], v[48:49]
	v_pk_mul_f32 v[42:43], v[34:35], v[42:43]
	v_pk_mul_f32 v[44:45], v[36:37], v[44:45]
	v_cvt_pk_bf16_f32 v46, v46, v47
	v_cvt_pk_bf16_f32 v47, v48, v49
	v_cvt_pk_bf16_f32 v48, v42, v43
	v_cvt_pk_bf16_f32 v49, v44, v45
	s_movk_i32 s14, 0x5000
	v_lshl_add_u64 v[118:119], v[130:131], 0, s[14:15]
	v_mul_f32_e32 v140, 0xbfb8aa3b, v138
	v_mul_f32_e32 v142, v138, v138
	v_pk_mul_f32 v[22:23], v[30:31], v[22:23]
	v_pk_mul_f32 v[24:25], v[32:33], v[24:25]
	v_pk_mul_f32 v[18:19], v[26:27], v[18:19]
	v_pk_mul_f32 v[20:21], v[28:29], v[20:21]
	v_pk_mul_f32 v[30:31], v[30:31], v[140:141] op_sel_hi:[1,0]
	v_pk_mul_f32 v[32:33], v[32:33], v[140:141] op_sel_hi:[1,0]
	v_pk_mul_f32 v[26:27], v[26:27], v[140:141] op_sel_hi:[1,0]
	v_pk_mul_f32 v[28:29], v[28:29], v[140:141] op_sel_hi:[1,0]
	v_exp_f32_e32 v30, v30
	v_exp_f32_e32 v31, v31
	v_exp_f32_e32 v32, v32
	v_exp_f32_e32 v33, v33
	v_exp_f32_e32 v26, v26
	v_exp_f32_e32 v27, v27
	v_exp_f32_e32 v28, v28
	v_exp_f32_e32 v29, v29
	v_pk_add_f32 v[30:31], v[30:31], v[144:145]
	v_pk_add_f32 v[32:33], v[32:33], v[144:145]
	v_pk_add_f32 v[26:27], v[26:27], v[144:145]
	v_pk_add_f32 v[28:29], v[28:29], v[144:145]
	v_rcp_f32_e32 v30, v30
	v_rcp_f32_e32 v31, v31
	v_rcp_f32_e32 v32, v32
	v_rcp_f32_e32 v33, v33
	v_rcp_f32_e32 v26, v26
	v_rcp_f32_e32 v27, v27
	v_rcp_f32_e32 v28, v28
	v_rcp_f32_e32 v29, v29
	v_pk_mul_f32 v[30:31], v[142:143], v[30:31] op_sel_hi:[0,1]
	v_pk_mul_f32 v[32:33], v[142:143], v[32:33] op_sel_hi:[0,1]
	v_pk_mul_f32 v[26:27], v[142:143], v[26:27] op_sel_hi:[0,1]
	v_pk_mul_f32 v[28:29], v[142:143], v[28:29] op_sel_hi:[0,1]
	v_pk_mul_f32 v[30:31], v[22:23], v[30:31]
	v_pk_mul_f32 v[32:33], v[24:25], v[32:33]
	v_pk_mul_f32 v[26:27], v[18:19], v[26:27]
	v_pk_mul_f32 v[28:29], v[20:21], v[28:29]
	v_cvt_pk_bf16_f32 v30, v30, v31
	v_cvt_pk_bf16_f32 v31, v32, v33
	v_cvt_pk_bf16_f32 v32, v26, v27
	v_cvt_pk_bf16_f32 v33, v28, v29
	v_mul_f32_e32 v140, 0xbfb8aa3b, v139
	v_mul_f32_e32 v142, v139, v139
	v_pk_mul_f32 v[6:7], v[14:15], v[6:7]
	v_pk_mul_f32 v[8:9], v[16:17], v[8:9]
	v_pk_mul_f32 v[2:3], v[10:11], v[2:3]
	v_pk_mul_f32 v[4:5], v[12:13], v[4:5]
	v_pk_mul_f32 v[14:15], v[14:15], v[140:141] op_sel_hi:[1,0]
	v_pk_mul_f32 v[16:17], v[16:17], v[140:141] op_sel_hi:[1,0]
	v_pk_mul_f32 v[10:11], v[10:11], v[140:141] op_sel_hi:[1,0]
	v_pk_mul_f32 v[12:13], v[12:13], v[140:141] op_sel_hi:[1,0]
	v_exp_f32_e32 v14, v14
	v_exp_f32_e32 v15, v15
	v_exp_f32_e32 v16, v16
	v_exp_f32_e32 v17, v17
	v_exp_f32_e32 v10, v10
	v_exp_f32_e32 v11, v11
	v_exp_f32_e32 v12, v12
	v_exp_f32_e32 v13, v13
	v_pk_add_f32 v[14:15], v[14:15], v[144:145]
	v_pk_add_f32 v[16:17], v[16:17], v[144:145]
	v_pk_add_f32 v[10:11], v[10:11], v[144:145]
	v_pk_add_f32 v[12:13], v[12:13], v[144:145]
	v_rcp_f32_e32 v14, v14
	v_rcp_f32_e32 v15, v15
	v_rcp_f32_e32 v16, v16
	v_rcp_f32_e32 v17, v17
	v_rcp_f32_e32 v10, v10
	v_rcp_f32_e32 v11, v11
	v_rcp_f32_e32 v12, v12
	v_rcp_f32_e32 v13, v13
	v_pk_mul_f32 v[14:15], v[142:143], v[14:15] op_sel_hi:[0,1]
	v_pk_mul_f32 v[16:17], v[142:143], v[16:17] op_sel_hi:[0,1]
	v_pk_mul_f32 v[10:11], v[142:143], v[10:11] op_sel_hi:[0,1]
	v_pk_mul_f32 v[12:13], v[142:143], v[12:13] op_sel_hi:[0,1]
	v_pk_mul_f32 v[14:15], v[6:7], v[14:15]
	v_pk_mul_f32 v[16:17], v[8:9], v[16:17]
	v_pk_mul_f32 v[10:11], v[2:3], v[10:11]
	v_pk_mul_f32 v[12:13], v[4:5], v[12:13]
	v_cvt_pk_bf16_f32 v14, v14, v15
	v_cvt_pk_bf16_f32 v15, v16, v17
	v_cvt_pk_bf16_f32 v16, v10, v11
	v_cvt_pk_bf16_f32 v17, v12, v13
	s_waitcnt vmcnt(0)
	global_store_dwordx4 v[130:131], v[126:129], off
	global_store_dwordx4 v[130:131], v[110:113], off offset:2048
	global_store_dwordx4 v[114:115], v[94:97], off
	global_store_dwordx4 v[114:115], v[78:81], off offset:2048
	global_store_dwordx4 v[116:117], v[62:65], off
	global_store_dwordx4 v[116:117], v[46:49], off offset:2048
	global_store_dwordx4 v[118:119], v[30:33], off
	global_store_dwordx4 v[118:119], v[14:17], off offset:2048
	s_and_saveexec_b64 s[44:45], s[88:89]
	s_cbranch_execz .LBB0_544
	s_waitcnt lgkmcnt(0)
	v_pk_add_f32 v[2:3], v[160:161], v[158:159]
	s_lshl_b32 s6, s36, 10
	v_add_f32_e32 v0, v2, v3
	v_fma_f32 v0, s62, v0, v195
	v_cmp_gt_f32_e32 vcc, s57, v0
	v_mul_f32_e32 v2, 0x4b800000, v0
	s_and_b32 s6, s6, 0x400
	v_cndmask_b32_e32 v0, v0, v2, vcc
	v_rsq_f32_e32 v0, v0
	s_nop 0
	v_mul_f32_e32 v2, 0x45800000, v0
	v_cndmask_b32_e32 v0, v0, v2, vcc
	v_add_u32_e32 v2, s6, v176
	ds_write_b32 v2, v0
	s_branch .LBB0_544
